# HGRN pass B: the unit epilogue's output-gate loads issued before the time recurrence instead of behind vmcnt(0)
# speedup vs baseline: 1.0062x; 1.0043x over previous
.LBB0_427:
	s_lshl_b32 s1, s7, 5
	s_and_b32 s1, s1, 0xffffff80
	v_add_u32_e32 v104, s1, v130
	s_waitcnt lgkmcnt(0)
	v_mov_b64_e32 v[48:49], s[14:15]
	v_mad_i64_i32 v[48:49], s[10:11], v104, s75, v[48:49]
	s_lshl_b32 s40, s6, 2
	v_lshl_add_u64 v[48:49], v[48:49], 0, s[40:41]
	v_lshlrev_b32_e32 v160, 2, v98
	v_lshl_add_u64 v[48:49], v[48:49], 0, v[160:161]
	s_barrier
	ds_read_b128 v[64:67], v132 offset:32768
	ds_read_b128 v[60:63], v132 offset:32784
	ds_read_b128 v[56:59], v132 offset:32800
	ds_read_b128 v[52:55], v132 offset:32816
	s_nop 0
	s_nop 0
	s_nop 0
	s_nop 0
	s_nop 0
	v_ashrrev_i32_e32 v105, 31, v104
	s_lshl_b32 s40, s6, 1
	v_lshlrev_b32_e32 v160, 1, v98
	s_waitcnt lgkmcnt(0)
	v_pk_mul_f32 v[108:109], v[52:53], v[52:53]
	v_pk_mul_f32 v[106:107], v[54:55], v[54:55]
	s_mov_b32 s7, s18
	s_waitcnt vmcnt(0)
	v_mov_b32_e32 v84, v240
	v_mov_b32_e32 v85, v241
	v_mov_b32_e32 v86, v242
	v_mov_b32_e32 v87, v243
	v_mov_b32_e32 v88, v244
	v_mov_b32_e32 v89, v245
	v_mov_b32_e32 v90, v246
	v_mov_b32_e32 v91, v247
	v_mov_b32_e32 v92, v248
	v_mov_b32_e32 v93, v249
	v_mov_b32_e32 v94, v250
	v_mov_b32_e32 v95, v251
	v_mov_b32_e32 v48, v236
	v_mov_b32_e32 v49, v237
	v_mov_b32_e32 v50, v238
	v_mov_b32_e32 v51, v239
	v_mul_f32_e32 v68, 0xbfb8aa3b, v48
	v_mul_f32_e32 v111, 0xbfb8aa3b, v49
	v_exp_f32_e32 v110, v68
	v_exp_f32_e32 v111, v111
	global_load_dwordx4 v[68:71], v[100:101], off offset:48
	global_load_dwordx4 v[72:75], v[100:101], off offset:32
	global_load_dwordx4 v[76:79], v[100:101], off offset:16
	global_load_dwordx4 v[80:83], v[100:101], off
	v_pk_add_f32 v[110:111], v[110:111], 1.0 op_sel_hi:[1,0]
	s_nop 0
	v_div_scale_f32 v112, s[10:11], v111, v111, 1.0
	v_rcp_f32_e32 v113, v112
	s_nop 0
	v_fma_f32 v114, -v112, v113, 1.0
	v_fmac_f32_e32 v113, v114, v113
	v_div_scale_f32 v114, vcc, 1.0, v111, 1.0
	v_mul_f32_e32 v115, v114, v113
	v_fma_f32 v116, -v112, v115, v114
	v_fmac_f32_e32 v115, v116, v113
	v_fma_f32 v112, -v112, v115, v114
	v_div_fmas_f32 v112, v112, v113, v115
	v_div_fixup_f32 v111, v112, v111, 1.0
	v_div_scale_f32 v112, s[10:11], v110, v110, 1.0
	v_rcp_f32_e32 v113, v112
	s_nop 0
	v_fma_f32 v114, -v112, v113, 1.0
	v_fmac_f32_e32 v113, v114, v113
	v_div_scale_f32 v114, vcc, 1.0, v110, 1.0
	v_mul_f32_e32 v115, v114, v113
	v_fma_f32 v116, -v112, v115, v114
	v_fmac_f32_e32 v115, v116, v113
	v_fma_f32 v112, -v112, v115, v114
	v_div_fmas_f32 v112, v112, v113, v115
	v_div_fixup_f32 v110, v112, v110, 1.0
	v_mul_f32_e32 v112, 0xbfb8aa3b, v94
	v_mul_f32_e32 v113, 0xbfb8aa3b, v95
	v_exp_f32_e32 v112, v112
	v_exp_f32_e32 v113, v113
	v_pk_mul_f32 v[48:49], v[48:49], v[110:111]
	v_pk_mul_f32 v[110:111], v[58:59], v[58:59]
	v_pk_add_f32 v[112:113], v[112:113], 1.0 op_sel_hi:[1,0]
	s_nop 0
	v_div_scale_f32 v114, s[10:11], v113, v113, 1.0
	v_rcp_f32_e32 v115, v114
	s_nop 0
	v_fma_f32 v116, -v114, v115, 1.0
	v_fmac_f32_e32 v115, v116, v115
	v_div_scale_f32 v116, vcc, 1.0, v113, 1.0
	v_mul_f32_e32 v117, v116, v115
	v_fma_f32 v141, -v114, v117, v116
	v_fmac_f32_e32 v117, v141, v115
	v_fma_f32 v114, -v114, v117, v116
	v_div_fmas_f32 v114, v114, v115, v117
	v_div_fixup_f32 v113, v114, v113, 1.0
	v_div_scale_f32 v114, s[10:11], v112, v112, 1.0
	v_rcp_f32_e32 v115, v114
	s_nop 0
	v_fma_f32 v116, -v114, v115, 1.0
	v_fmac_f32_e32 v115, v116, v115
	v_div_scale_f32 v116, vcc, 1.0, v112, 1.0
	v_mul_f32_e32 v117, v116, v115
	v_fma_f32 v141, -v114, v117, v116
	v_fmac_f32_e32 v117, v141, v115
	v_fma_f32 v114, -v114, v117, v116
	v_div_fmas_f32 v114, v114, v115, v117
	v_div_fixup_f32 v112, v114, v112, 1.0
	v_mul_f32_e32 v114, 0xbfb8aa3b, v92
	v_mul_f32_e32 v115, 0xbfb8aa3b, v93
	v_exp_f32_e32 v114, v114
	v_exp_f32_e32 v115, v115
	v_pk_mul_f32 v[94:95], v[94:95], v[112:113]
	v_pk_mul_f32 v[112:113], v[56:57], v[56:57]
	v_pk_add_f32 v[114:115], v[114:115], 1.0 op_sel_hi:[1,0]
	s_nop 0
	v_div_scale_f32 v116, s[10:11], v115, v115, 1.0
	v_rcp_f32_e32 v117, v116
	s_nop 0
	v_fma_f32 v141, -v116, v117, 1.0
	v_fmac_f32_e32 v117, v141, v117
	v_div_scale_f32 v141, vcc, 1.0, v115, 1.0
	v_mul_f32_e32 v142, v141, v117
	v_fma_f32 v143, -v116, v142, v141
	v_fmac_f32_e32 v142, v143, v117
	v_fma_f32 v116, -v116, v142, v141
	v_div_fmas_f32 v116, v116, v117, v142
	v_div_fixup_f32 v115, v116, v115, 1.0
	v_div_scale_f32 v116, s[10:11], v114, v114, 1.0
	v_rcp_f32_e32 v117, v116
	s_nop 0
	v_fma_f32 v141, -v116, v117, 1.0
	v_fmac_f32_e32 v117, v141, v117
	v_div_scale_f32 v141, vcc, 1.0, v114, 1.0
	v_mul_f32_e32 v142, v141, v117
	v_fma_f32 v143, -v116, v142, v141
	v_fmac_f32_e32 v142, v143, v117
	v_fma_f32 v116, -v116, v142, v141
	v_div_fmas_f32 v116, v116, v117, v142
	v_div_fixup_f32 v114, v116, v114, 1.0
	v_mul_f32_e32 v116, 0xbfb8aa3b, v90
	v_mul_f32_e32 v117, 0xbfb8aa3b, v91
	v_exp_f32_e32 v116, v116
	v_exp_f32_e32 v117, v117
	v_pk_mul_f32 v[92:93], v[92:93], v[114:115]
	v_pk_mul_f32 v[114:115], v[62:63], v[62:63]
	v_pk_add_f32 v[116:117], v[116:117], 1.0 op_sel_hi:[1,0]
	s_nop 0
	v_div_scale_f32 v141, s[10:11], v117, v117, 1.0
	v_rcp_f32_e32 v142, v141
	s_nop 0
	v_fma_f32 v143, -v141, v142, 1.0
	v_fmac_f32_e32 v142, v143, v142
	v_div_scale_f32 v143, vcc, 1.0, v117, 1.0
	v_mul_f32_e32 v144, v143, v142
	v_fma_f32 v145, -v141, v144, v143
	v_fmac_f32_e32 v144, v145, v142
	v_fma_f32 v141, -v141, v144, v143
	v_div_fmas_f32 v141, v141, v142, v144
	v_div_fixup_f32 v117, v141, v117, 1.0
	v_div_scale_f32 v141, s[10:11], v116, v116, 1.0
	v_rcp_f32_e32 v142, v141
	s_nop 0
	v_fma_f32 v143, -v141, v142, 1.0
	v_fmac_f32_e32 v142, v143, v142
	v_div_scale_f32 v143, vcc, 1.0, v116, 1.0
	v_mul_f32_e32 v144, v143, v142
	v_fma_f32 v145, -v141, v144, v143
	v_fmac_f32_e32 v144, v145, v142
	v_fma_f32 v141, -v141, v144, v143
	v_div_fmas_f32 v141, v141, v142, v144
	v_div_fixup_f32 v116, v141, v116, 1.0
	v_mul_f32_e32 v141, 0xbfb8aa3b, v88
	v_exp_f32_e32 v142, v141
	v_mul_f32_e32 v141, 0xbfb8aa3b, v89
	v_exp_f32_e32 v143, v141
	v_pk_mul_f32 v[90:91], v[90:91], v[116:117]
	v_pk_mul_f32 v[116:117], v[60:61], v[60:61]
	v_pk_add_f32 v[142:143], v[142:143], 1.0 op_sel_hi:[1,0]
	s_nop 0
	v_div_scale_f32 v141, s[10:11], v143, v143, 1.0
	v_rcp_f32_e32 v144, v141
	s_nop 0
	v_fma_f32 v145, -v141, v144, 1.0
	v_fmac_f32_e32 v144, v145, v144
	v_div_scale_f32 v145, vcc, 1.0, v143, 1.0
	v_mul_f32_e32 v146, v145, v144
	v_fma_f32 v147, -v141, v146, v145
	v_fmac_f32_e32 v146, v147, v144
	v_fma_f32 v141, -v141, v146, v145
	v_div_fmas_f32 v141, v141, v144, v146
	v_div_fixup_f32 v143, v141, v143, 1.0
	v_div_scale_f32 v141, s[10:11], v142, v142, 1.0
	v_rcp_f32_e32 v144, v141
	s_nop 0
	v_fma_f32 v145, -v141, v144, 1.0
	v_fmac_f32_e32 v144, v145, v144
	v_div_scale_f32 v145, vcc, 1.0, v142, 1.0
	v_mul_f32_e32 v146, v145, v144
	v_fma_f32 v147, -v141, v146, v145
	v_fmac_f32_e32 v146, v147, v144
	v_fma_f32 v141, -v141, v146, v145
	v_div_fmas_f32 v141, v141, v144, v146
	v_div_fixup_f32 v142, v141, v142, 1.0
	v_mul_f32_e32 v141, 0xbfb8aa3b, v86
	v_exp_f32_e32 v144, v141
	v_mul_f32_e32 v141, 0xbfb8aa3b, v87
	v_exp_f32_e32 v145, v141
	v_pk_mul_f32 v[88:89], v[88:89], v[142:143]
	v_pk_mul_f32 v[142:143], v[66:67], v[66:67]
	v_pk_add_f32 v[144:145], v[144:145], 1.0 op_sel_hi:[1,0]
	s_nop 0
	v_div_scale_f32 v141, s[10:11], v145, v145, 1.0
	v_rcp_f32_e32 v146, v141
	s_nop 0
	v_fma_f32 v147, -v141, v146, 1.0
	v_fmac_f32_e32 v146, v147, v146
	v_div_scale_f32 v147, vcc, 1.0, v145, 1.0
	v_mul_f32_e32 v148, v147, v146
	v_fma_f32 v149, -v141, v148, v147
	v_fmac_f32_e32 v148, v149, v146
	v_fma_f32 v141, -v141, v148, v147
	v_div_fmas_f32 v141, v141, v146, v148
	v_div_fixup_f32 v145, v141, v145, 1.0
	v_div_scale_f32 v141, s[10:11], v144, v144, 1.0
	v_rcp_f32_e32 v146, v141
	s_nop 0
	v_fma_f32 v147, -v141, v146, 1.0
	v_fmac_f32_e32 v146, v147, v146
	v_div_scale_f32 v147, vcc, 1.0, v144, 1.0
	v_mul_f32_e32 v148, v147, v146
	v_fma_f32 v149, -v141, v148, v147
	v_fmac_f32_e32 v148, v149, v146
	v_fma_f32 v141, -v141, v148, v147
	v_div_fmas_f32 v141, v141, v146, v148
	v_div_fixup_f32 v144, v141, v144, 1.0
	v_mul_f32_e32 v141, 0xbfb8aa3b, v84
	v_exp_f32_e32 v146, v141
	v_mul_f32_e32 v141, 0xbfb8aa3b, v85
	v_exp_f32_e32 v147, v141
	v_pk_mul_f32 v[86:87], v[86:87], v[144:145]
	v_pk_mul_f32 v[144:145], v[64:65], v[64:65]
	v_pk_add_f32 v[146:147], v[146:147], 1.0 op_sel_hi:[1,0]
	s_nop 0
	v_div_scale_f32 v141, s[10:11], v147, v147, 1.0
	v_rcp_f32_e32 v148, v141
	s_nop 0
	v_fma_f32 v149, -v141, v148, 1.0
	v_fmac_f32_e32 v148, v149, v148
	v_div_scale_f32 v149, vcc, 1.0, v147, 1.0
	v_mul_f32_e32 v150, v149, v148
	v_fma_f32 v151, -v141, v150, v149
	v_fmac_f32_e32 v150, v151, v148
	v_fma_f32 v141, -v141, v150, v149
	v_div_fmas_f32 v141, v141, v148, v150
	v_div_fixup_f32 v147, v141, v147, 1.0
	v_div_scale_f32 v141, s[10:11], v146, v146, 1.0
	v_rcp_f32_e32 v148, v141
	s_nop 0
	v_fma_f32 v149, -v141, v148, 1.0
	v_fmac_f32_e32 v148, v149, v148
	v_div_scale_f32 v149, vcc, 1.0, v146, 1.0
	v_mul_f32_e32 v150, v149, v148
	v_fma_f32 v151, -v141, v150, v149
	v_fmac_f32_e32 v150, v151, v148
	v_fma_f32 v141, -v141, v150, v149
	v_div_fmas_f32 v141, v141, v148, v150
	v_div_fixup_f32 v146, v141, v146, 1.0
	v_add_f32_e32 v141, v144, v145
	v_add_f32_e32 v141, v141, v142
	v_add_f32_e32 v141, v141, v143
	v_add_f32_e32 v116, v141, v116
	v_add_f32_e32 v116, v116, v117
	v_add_f32_e32 v114, v116, v114
	v_add_f32_e32 v114, v114, v115
	v_add_f32_e32 v112, v114, v112
	v_add_f32_e32 v112, v112, v113
	v_add_f32_e32 v110, v112, v110
	v_add_f32_e32 v110, v110, v111
	v_add_f32_e32 v108, v110, v108
	v_add_f32_e32 v108, v108, v109
	v_add_f32_e32 v106, v108, v106
	v_add_f32_e32 v106, v106, v107
	v_pk_mul_f32 v[84:85], v[84:85], v[146:147]
	s_nop 0
	v_add_f32_dpp v106, v106, v106 quad_perm:[1,0,3,2] row_mask:0xf bank_mask:0xf bound_ctrl:1
	s_nop 1
	v_add_f32_dpp v106, v106, v106 quad_perm:[2,3,0,1] row_mask:0xf bank_mask:0xf bound_ctrl:1
	v_fmamk_f32 v106, v106, 0x3c800000, v182
	v_cmp_gt_f32_e32 vcc, s50, v106
	v_mul_f32_e32 v107, 0x4f800000, v106
	s_nop 0
	v_cndmask_b32_e32 v106, v106, v107, vcc
	v_sqrt_f32_e32 v107, v106
	s_nop 0
	v_add_u32_e32 v108, -1, v107
	v_fma_f32 v109, -v108, v107, v106
	v_cmp_ge_f32_e64 s[10:11], 0, v109
	v_add_u32_e32 v109, 1, v107
	s_nop 0
	v_cndmask_b32_e64 v108, v107, v108, s[10:11]
	v_fma_f32 v107, -v109, v107, v106
	v_cmp_lt_f32_e64 s[10:11], 0, v107
	s_nop 1
	v_cndmask_b32_e64 v107, v108, v109, s[10:11]
	v_mul_f32_e32 v108, 0x37800000, v107
	v_cndmask_b32_e32 v107, v107, v108, vcc
	v_cmp_class_f32_e32 vcc, v106, v183
	s_nop 1
	v_cndmask_b32_e32 v106, v107, v106, vcc
	v_div_scale_f32 v107, s[10:11], v106, v106, 1.0
	v_rcp_f32_e32 v108, v107
	s_nop 0
	v_fma_f32 v109, -v107, v108, 1.0
	v_fmac_f32_e32 v108, v109, v108
	v_div_scale_f32 v109, vcc, 1.0, v106, 1.0
	v_mul_f32_e32 v110, v109, v108
	v_fma_f32 v111, -v107, v110, v109
	v_fmac_f32_e32 v110, v111, v108
	v_fma_f32 v107, -v107, v110, v109
	v_div_fmas_f32 v107, v107, v108, v110
	v_div_fixup_f32 v106, v107, v106, 1.0
	v_pk_mul_f32 v[56:57], v[56:57], v[106:107] op_sel_hi:[1,0]
	v_pk_mul_f32 v[58:59], v[58:59], v[106:107] op_sel_hi:[1,0]
	v_pk_mul_f32 v[52:53], v[52:53], v[106:107] op_sel_hi:[1,0]
	s_waitcnt vmcnt(2)
	v_pk_mul_f32 v[56:57], v[56:57], v[72:73]
	v_pk_mul_f32 v[58:59], v[58:59], v[74:75]
	v_pk_mul_f32 v[52:53], v[52:53], v[68:69]
	v_pk_mul_f32 v[56:57], v[56:57], v[92:93]
	v_pk_mul_f32 v[58:59], v[58:59], v[94:95]
	v_pk_mul_f32 v[48:49], v[52:53], v[48:49]
	v_cvt_pk_bf16_f32 v56, v56, v57
	v_cvt_pk_bf16_f32 v57, v58, v59
	v_cvt_pk_bf16_f32 v58, v48, v49
	v_mul_f32_e32 v48, 0xbfb8aa3b, v50
	v_mul_f32_e32 v49, 0xbfb8aa3b, v51
	v_exp_f32_e32 v48, v48
	v_exp_f32_e32 v49, v49
	v_pk_mul_f32 v[52:53], v[54:55], v[106:107] op_sel_hi:[1,0]
	v_pk_mul_f32 v[64:65], v[64:65], v[106:107] op_sel_hi:[1,0]
	v_pk_mul_f32 v[66:67], v[66:67], v[106:107] op_sel_hi:[1,0]
	v_pk_add_f32 v[48:49], v[48:49], 1.0 op_sel_hi:[1,0]
	v_pk_mul_f32 v[60:61], v[60:61], v[106:107] op_sel_hi:[1,0]
	v_div_scale_f32 v54, s[10:11], v49, v49, 1.0
	v_rcp_f32_e32 v55, v54
	s_waitcnt vmcnt(0)
	v_pk_mul_f32 v[64:65], v[80:81], v[64:65]
	v_pk_mul_f32 v[66:67], v[66:67], v[82:83]
	v_pk_mul_f32 v[60:61], v[60:61], v[76:77]
	v_pk_mul_f32 v[64:65], v[84:85], v[64:65]
	v_pk_mul_f32 v[66:67], v[66:67], v[86:87]
	v_pk_mul_f32 v[60:61], v[60:61], v[88:89]
	v_cvt_pk_bf16_f32 v64, v64, v65
	v_cvt_pk_bf16_f32 v65, v66, v67
	v_cvt_pk_bf16_f32 v66, v60, v61
	v_pk_mul_f32 v[60:61], v[62:63], v[106:107] op_sel_hi:[1,0]
	v_fma_f32 v59, -v54, v55, 1.0
	v_pk_mul_f32 v[60:61], v[60:61], v[78:79]
	v_fmac_f32_e32 v55, v59, v55
	v_pk_mul_f32 v[60:61], v[60:61], v[90:91]
	v_div_scale_f32 v59, vcc, 1.0, v49, 1.0
	v_cvt_pk_bf16_f32 v67, v60, v61
	v_mul_f32_e32 v60, v59, v55
	v_fma_f32 v61, -v54, v60, v59
	v_fmac_f32_e32 v60, v61, v55
	v_fma_f32 v54, -v54, v60, v59
	v_div_fmas_f32 v54, v54, v55, v60
	v_div_fixup_f32 v49, v54, v49, 1.0
	v_div_scale_f32 v54, s[10:11], v48, v48, 1.0
	v_rcp_f32_e32 v55, v54
	v_pk_mul_f32 v[52:53], v[52:53], v[70:71]
	v_mov_b32_e32 v81, v140
	v_mov_b32_e32 v80, v139
	v_fma_f32 v59, -v54, v55, 1.0
	v_fmac_f32_e32 v55, v59, v55
	v_div_scale_f32 v59, vcc, 1.0, v48, 1.0
	v_mul_f32_e32 v60, v59, v55
	v_fma_f32 v61, -v54, v60, v59
	v_fmac_f32_e32 v60, v61, v55
	v_fma_f32 v54, -v54, v60, v59
	v_div_fmas_f32 v54, v54, v55, v60
	v_div_fixup_f32 v48, v54, v48, 1.0
	v_pk_mul_f32 v[48:49], v[50:51], v[48:49]
	s_and_b64 vcc, exec, s[20:21]
	v_pk_mul_f32 v[48:49], v[52:53], v[48:49]
	v_mov_b32_e32 v83, v138
	v_cvt_pk_bf16_f32 v59, v48, v49
	v_lshlrev_b64 v[48:49], 11, v[104:105]
	v_lshl_add_u64 v[48:49], s[16:17], 0, v[48:49]
	v_lshl_add_u64 v[48:49], v[48:49], 0, s[40:41]
	v_lshl_add_u64 v[48:49], v[48:49], 0, v[160:161]
	v_mov_b32_e32 v82, v137
	v_mov_b32_e32 v85, v136
	v_mov_b32_e32 v84, v135
	v_mov_b32_e32 v87, v134
	v_mov_b32_e32 v86, v133
	global_store_dwordx4 v[48:49], v[64:67], off
	global_store_dwordx4 v[48:49], v[56:59], off offset:16
	s_barrier
	s_cbranch_vccnz .LBB0_472

.LBB0_450:
	s_lshl_b32 s1, s7, 5
	s_and_b32 s1, s1, 0xffffff80
	v_add_u32_e32 v232, s1, v130
	v_mov_b64_e32 v[234:235], s[14:15]
	v_mad_i64_i32 v[234:235], s[10:11], v232, s75, v[234:235]
	s_lshl_b32 s40, s6, 2
	v_lshl_add_u64 v[234:235], v[234:235], 0, s[40:41]
	v_lshlrev_b32_e32 v152, 2, v98
	v_mov_b32_e32 v153, 0
	v_lshl_add_u64 v[234:235], v[234:235], 0, v[152:153]
	global_load_dwordx4 v[240:243], v[234:235], off offset:3072
	global_load_dwordx4 v[244:247], v[234:235], off offset:3088
	global_load_dwordx4 v[248:251], v[234:235], off offset:3104
	global_load_dwordx4 v[236:239], v[234:235], off offset:3120
	v_mov_b32_e32 v113, v121
	v_mov_b32_e32 v114, v131
	v_mov_b32_e32 v115, v123
	v_add_u32_e32 v112, 0x10000, v131
	s_nop 0
	v_cndmask_b32_e64 v112, v112, v131, s[8:9]
	ds_read_b128 v[60:63], v113 offset:0
	ds_read_b128 v[56:59], v113 offset:16
	ds_read_b32 v88, v114 offset:0
	ds_read_b128 v[52:55], v115 offset:0
	ds_read_b128 v[48:51], v115 offset:16
	ds_read_b128 v[64:67], v113 offset:256
	ds_read_b128 v[68:71], v113 offset:272
	ds_read_b32 v90, v114 offset:256
	ds_read_b128 v[72:75], v115 offset:256
	ds_read_b128 v[76:79], v115 offset:272
	s_waitcnt lgkmcnt(5)
	v_pk_add_f32 v[92:93], v[86:87], v[88:89] op_sel_hi:[1,0] neg_lo:[0,1] neg_hi:[0,1]
	v_pk_add_f32 v[94:95], v[84:85], v[88:89] op_sel_hi:[1,0] neg_lo:[0,1] neg_hi:[0,1]
	v_pk_add_f32 v[104:105], v[82:83], v[88:89] op_sel_hi:[1,0] neg_lo:[0,1] neg_hi:[0,1]
	v_pk_add_f32 v[106:107], v[80:81], v[88:89] op_sel_hi:[1,0] neg_lo:[0,1] neg_hi:[0,1]
	v_pk_fma_f32 v[86:87], v[60:61], v[92:93], v[88:89] op_sel_hi:[1,1,0]
	v_pk_fma_f32 v[84:85], v[62:63], v[94:95], v[88:89] op_sel_hi:[1,1,0]
	v_pk_fma_f32 v[82:83], v[56:57], v[104:105], v[88:89] op_sel_hi:[1,1,0]
	v_pk_fma_f32 v[80:81], v[58:59], v[106:107], v[88:89] op_sel_hi:[1,1,0]
	s_waitcnt lgkmcnt(0)
	s_mov_b32 s1, 0
